# S5 half rewritten: U staging loads batched, stage1 and stage3 LDS->MFMA software pipelined, B operands preloaded
# speedup vs baseline: 1.0018x; 1.0018x over previous
.LBB0_656:
	v_lshl_add_u64 v[238:239], v[138:139], 0, s[74:75]
	global_load_dwordx4 v[2:5], v[238:239], off
	global_load_dwordx4 v[6:9], v[238:239], off offset:64
	global_load_dwordx4 v[10:13], v[238:239], off offset:128
	global_load_dwordx4 v[14:17], v[238:239], off offset:192
	global_load_dwordx4 v[18:21], v[238:239], off offset:256
	global_load_dwordx4 v[22:25], v[238:239], off offset:320
	global_load_dwordx4 v[26:29], v[238:239], off offset:384
	global_load_dwordx4 v[30:33], v[238:239], off offset:448
	v_mov_b32_e32 v237, 0
	v_add_lshl_u32 v236, s91, v188, 9
	v_lshl_add_u64 v[220:221], v[236:237], 0, v[142:143]
	v_add_lshl_u32 v236, s91, v190, 9
	v_lshl_add_u64 v[222:223], v[236:237], 0, v[142:143]
	v_add_lshl_u32 v236, s91, v191, 9
	v_lshl_add_u64 v[224:225], v[236:237], 0, v[142:143]
	v_add_lshl_u32 v236, s91, v192, 9
	v_lshl_add_u64 v[226:227], v[236:237], 0, v[142:143]
	v_add_lshl_u32 v236, s91, v193, 9
	v_lshl_add_u64 v[228:229], v[236:237], 0, v[142:143]
	v_add_lshl_u32 v236, s91, v194, 9
	v_lshl_add_u64 v[230:231], v[236:237], 0, v[142:143]
	v_add_lshl_u32 v236, s91, v195, 9
	v_lshl_add_u64 v[232:233], v[236:237], 0, v[142:143]
	v_add_lshl_u32 v236, s91, v196, 9
	v_lshl_add_u64 v[234:235], v[236:237], 0, v[142:143]
	global_load_dwordx4 v[34:37], v[220:221], off
	global_load_dwordx4 v[38:41], v[222:223], off
	global_load_dwordx4 v[42:45], v[224:225], off
	global_load_dwordx4 v[46:49], v[226:227], off
	global_load_dwordx4 v[50:53], v[228:229], off
	global_load_dwordx4 v[54:57], v[230:231], off
	global_load_dwordx4 v[58:61], v[232:233], off
	global_load_dwordx4 v[62:65], v[234:235], off
	s_waitcnt vmcnt(7)
	ds_write_b128 v200, v[34:37]
	s_waitcnt vmcnt(6)
	ds_write_b128 v201, v[38:41]
	s_waitcnt vmcnt(5)
	ds_write_b128 v202, v[42:45]
	s_waitcnt vmcnt(4)
	ds_write_b128 v203, v[46:49]
	s_waitcnt vmcnt(3)
	ds_write_b128 v214, v[50:53]
	s_waitcnt vmcnt(2)
	ds_write_b128 v215, v[54:57]
	s_waitcnt vmcnt(1)
	ds_write_b128 v216, v[58:61]
	s_waitcnt vmcnt(0)
	ds_write_b128 v217, v[62:65]
	s_waitcnt lgkmcnt(0)
	s_barrier
	ds_read_b128 v[126:129], v197
	ds_read_b128 v[122:125], v197 offset:64
	ds_read_b128 v[118:121], v197 offset:128
	ds_read_b128 v[106:109], v197 offset:192
	ds_read_b128 v[98:101], v197 offset:256
	ds_read_b128 v[90:93], v197 offset:320
	ds_read_b128 v[82:85], v197 offset:384
	ds_read_b128 v[74:77], v197 offset:448
	s_waitcnt lgkmcnt(0)
	ds_read_b128 v[130:133], v197 offset:8448
	ds_read_b128 v[134:137], v197 offset:8512
	ds_read_b128 v[220:223], v197 offset:8576
	ds_read_b128 v[224:227], v197 offset:8640
	ds_read_b128 v[228:231], v197 offset:8704
	ds_read_b128 v[232:235], v197 offset:8768
	ds_read_b128 v[236:239], v197 offset:8832
	ds_read_b128 v[240:243], v197 offset:8896
	v_mfma_f32_16x16x32_bf16 v[34:37], v[126:129], v[2:5], 0
	v_mfma_f32_16x16x32_bf16 v[34:37], v[122:125], v[6:9], v[34:37]
	v_mfma_f32_16x16x32_bf16 v[34:37], v[118:121], v[10:13], v[34:37]
	v_mfma_f32_16x16x32_bf16 v[34:37], v[106:109], v[14:17], v[34:37]
	v_mfma_f32_16x16x32_bf16 v[34:37], v[98:101], v[18:21], v[34:37]
	v_mfma_f32_16x16x32_bf16 v[34:37], v[90:93], v[22:25], v[34:37]
	v_mfma_f32_16x16x32_bf16 v[34:37], v[82:85], v[26:29], v[34:37]
	v_mfma_f32_16x16x32_bf16 v[34:37], v[74:77], v[30:33], v[34:37]
	s_waitcnt lgkmcnt(0)
	ds_read_b128 v[126:129], v197 offset:16896
	ds_read_b128 v[122:125], v197 offset:16960
	ds_read_b128 v[118:121], v197 offset:17024
	ds_read_b128 v[106:109], v197 offset:17088
	ds_read_b128 v[98:101], v197 offset:17152
	ds_read_b128 v[90:93], v197 offset:17216
	ds_read_b128 v[82:85], v197 offset:17280
	ds_read_b128 v[74:77], v197 offset:17344
	v_mfma_f32_16x16x32_bf16 v[38:41], v[130:133], v[2:5], 0
	v_mfma_f32_16x16x32_bf16 v[38:41], v[134:137], v[6:9], v[38:41]
	v_mfma_f32_16x16x32_bf16 v[38:41], v[220:223], v[10:13], v[38:41]
	v_mfma_f32_16x16x32_bf16 v[38:41], v[224:227], v[14:17], v[38:41]
	v_mfma_f32_16x16x32_bf16 v[38:41], v[228:231], v[18:21], v[38:41]
	v_mfma_f32_16x16x32_bf16 v[38:41], v[232:235], v[22:25], v[38:41]
	v_mfma_f32_16x16x32_bf16 v[38:41], v[236:239], v[26:29], v[38:41]
	v_mfma_f32_16x16x32_bf16 v[38:41], v[240:243], v[30:33], v[38:41]
	ds_write_b32 v218, v34
	ds_write_b32 v218, v35 offset:528
	ds_write_b32 v218, v36 offset:1056
	ds_write_b32 v218, v37 offset:1584
	s_waitcnt lgkmcnt(4)
	ds_read_b128 v[130:133], v197 offset:25344
	ds_read_b128 v[134:137], v197 offset:25408
	ds_read_b128 v[220:223], v197 offset:25472
	ds_read_b128 v[224:227], v197 offset:25536
	ds_read_b128 v[228:231], v197 offset:25600
	ds_read_b128 v[232:235], v197 offset:25664
	ds_read_b128 v[236:239], v197 offset:25728
	ds_read_b128 v[240:243], v197 offset:25792
	v_mfma_f32_16x16x32_bf16 v[34:37], v[126:129], v[2:5], 0
	v_mfma_f32_16x16x32_bf16 v[34:37], v[122:125], v[6:9], v[34:37]
	v_mfma_f32_16x16x32_bf16 v[34:37], v[118:121], v[10:13], v[34:37]
	v_mfma_f32_16x16x32_bf16 v[34:37], v[106:109], v[14:17], v[34:37]
	v_mfma_f32_16x16x32_bf16 v[34:37], v[98:101], v[18:21], v[34:37]
	v_mfma_f32_16x16x32_bf16 v[34:37], v[90:93], v[22:25], v[34:37]
	v_mfma_f32_16x16x32_bf16 v[34:37], v[82:85], v[26:29], v[34:37]
	v_mfma_f32_16x16x32_bf16 v[34:37], v[74:77], v[30:33], v[34:37]
	ds_write_b32 v218, v38 offset:8448
	ds_write_b32 v218, v39 offset:8976
	ds_write_b32 v218, v40 offset:9504
	ds_write_b32 v218, v41 offset:10032
	s_waitcnt lgkmcnt(4)
	ds_read_b128 v[126:129], v197 offset:33792
	ds_read_b128 v[122:125], v197 offset:33856
	ds_read_b128 v[118:121], v197 offset:33920
	ds_read_b128 v[106:109], v197 offset:33984
	ds_read_b128 v[98:101], v197 offset:34048
	ds_read_b128 v[90:93], v197 offset:34112
	ds_read_b128 v[82:85], v197 offset:34176
	ds_read_b128 v[74:77], v197 offset:34240
	v_mfma_f32_16x16x32_bf16 v[38:41], v[130:133], v[2:5], 0
	v_mfma_f32_16x16x32_bf16 v[38:41], v[134:137], v[6:9], v[38:41]
	v_mfma_f32_16x16x32_bf16 v[38:41], v[220:223], v[10:13], v[38:41]
	v_mfma_f32_16x16x32_bf16 v[38:41], v[224:227], v[14:17], v[38:41]
	v_mfma_f32_16x16x32_bf16 v[38:41], v[228:231], v[18:21], v[38:41]
	v_mfma_f32_16x16x32_bf16 v[38:41], v[232:235], v[22:25], v[38:41]
	v_mfma_f32_16x16x32_bf16 v[38:41], v[236:239], v[26:29], v[38:41]
	v_mfma_f32_16x16x32_bf16 v[38:41], v[240:243], v[30:33], v[38:41]
	ds_write_b32 v218, v34 offset:16896
	ds_write_b32 v218, v35 offset:17424
	ds_write_b32 v218, v36 offset:17952
	ds_write_b32 v218, v37 offset:18480
	s_waitcnt lgkmcnt(4)
	ds_read_b128 v[130:133], v197 offset:42240
	ds_read_b128 v[134:137], v197 offset:42304
	ds_read_b128 v[220:223], v197 offset:42368
	ds_read_b128 v[224:227], v197 offset:42432
	ds_read_b128 v[228:231], v197 offset:42496
	ds_read_b128 v[232:235], v197 offset:42560
	ds_read_b128 v[236:239], v197 offset:42624
	ds_read_b128 v[240:243], v197 offset:42688
	v_mfma_f32_16x16x32_bf16 v[34:37], v[126:129], v[2:5], 0
	v_mfma_f32_16x16x32_bf16 v[34:37], v[122:125], v[6:9], v[34:37]
	v_mfma_f32_16x16x32_bf16 v[34:37], v[118:121], v[10:13], v[34:37]
	v_mfma_f32_16x16x32_bf16 v[34:37], v[106:109], v[14:17], v[34:37]
	v_mfma_f32_16x16x32_bf16 v[34:37], v[98:101], v[18:21], v[34:37]
	v_mfma_f32_16x16x32_bf16 v[34:37], v[90:93], v[22:25], v[34:37]
	v_mfma_f32_16x16x32_bf16 v[34:37], v[82:85], v[26:29], v[34:37]
	v_mfma_f32_16x16x32_bf16 v[34:37], v[74:77], v[30:33], v[34:37]
	ds_write_b32 v218, v38 offset:25344
	ds_write_b32 v218, v39 offset:25872
	ds_write_b32 v218, v40 offset:26400
	ds_write_b32 v218, v41 offset:26928
	s_waitcnt lgkmcnt(4)
	ds_read_b128 v[126:129], v197 offset:50688
	ds_read_b128 v[122:125], v197 offset:50752
	ds_read_b128 v[118:121], v197 offset:50816
	ds_read_b128 v[106:109], v197 offset:50880
	ds_read_b128 v[98:101], v197 offset:50944
	ds_read_b128 v[90:93], v197 offset:51008
	ds_read_b128 v[82:85], v197 offset:51072
	ds_read_b128 v[74:77], v197 offset:51136
	v_mfma_f32_16x16x32_bf16 v[38:41], v[130:133], v[2:5], 0
	v_mfma_f32_16x16x32_bf16 v[38:41], v[134:137], v[6:9], v[38:41]
	v_mfma_f32_16x16x32_bf16 v[38:41], v[220:223], v[10:13], v[38:41]
	v_mfma_f32_16x16x32_bf16 v[38:41], v[224:227], v[14:17], v[38:41]
	v_mfma_f32_16x16x32_bf16 v[38:41], v[228:231], v[18:21], v[38:41]
	v_mfma_f32_16x16x32_bf16 v[38:41], v[232:235], v[22:25], v[38:41]
	v_mfma_f32_16x16x32_bf16 v[38:41], v[236:239], v[26:29], v[38:41]
	v_mfma_f32_16x16x32_bf16 v[38:41], v[240:243], v[30:33], v[38:41]
	ds_write_b32 v218, v34 offset:33792
	ds_write_b32 v218, v35 offset:34320
	ds_write_b32 v218, v36 offset:34848
	ds_write_b32 v218, v37 offset:35376
	s_waitcnt lgkmcnt(4)
	ds_read_b128 v[130:133], v197 offset:59136
	ds_read_b128 v[134:137], v197 offset:59200
	ds_read_b128 v[220:223], v197 offset:59264
	ds_read_b128 v[224:227], v197 offset:59328
	ds_read_b128 v[228:231], v197 offset:59392
	ds_read_b128 v[232:235], v197 offset:59456
	ds_read_b128 v[236:239], v197 offset:59520
	ds_read_b128 v[240:243], v197 offset:59584
	v_mfma_f32_16x16x32_bf16 v[34:37], v[126:129], v[2:5], 0
	v_mfma_f32_16x16x32_bf16 v[34:37], v[122:125], v[6:9], v[34:37]
	v_mfma_f32_16x16x32_bf16 v[34:37], v[118:121], v[10:13], v[34:37]
	v_mfma_f32_16x16x32_bf16 v[34:37], v[106:109], v[14:17], v[34:37]
	v_mfma_f32_16x16x32_bf16 v[34:37], v[98:101], v[18:21], v[34:37]
	v_mfma_f32_16x16x32_bf16 v[34:37], v[90:93], v[22:25], v[34:37]
	v_mfma_f32_16x16x32_bf16 v[34:37], v[82:85], v[26:29], v[34:37]
	v_mfma_f32_16x16x32_bf16 v[34:37], v[74:77], v[30:33], v[34:37]
	ds_write_b32 v218, v38 offset:42240
	ds_write_b32 v218, v39 offset:42768
	ds_write_b32 v218, v40 offset:43296
	ds_write_b32 v218, v41 offset:43824
	s_waitcnt lgkmcnt(4)
	v_mfma_f32_16x16x32_bf16 v[38:41], v[130:133], v[2:5], 0
	v_mfma_f32_16x16x32_bf16 v[38:41], v[134:137], v[6:9], v[38:41]
	v_mfma_f32_16x16x32_bf16 v[38:41], v[220:223], v[10:13], v[38:41]
	v_mfma_f32_16x16x32_bf16 v[38:41], v[224:227], v[14:17], v[38:41]
	v_mfma_f32_16x16x32_bf16 v[38:41], v[228:231], v[18:21], v[38:41]
	v_mfma_f32_16x16x32_bf16 v[38:41], v[232:235], v[22:25], v[38:41]
	v_mfma_f32_16x16x32_bf16 v[38:41], v[236:239], v[26:29], v[38:41]
	v_mfma_f32_16x16x32_bf16 v[38:41], v[240:243], v[30:33], v[38:41]
	ds_write_b32 v218, v34 offset:50688
	ds_write_b32 v218, v35 offset:51216
	ds_write_b32 v218, v36 offset:51744
	ds_write_b32 v218, v37 offset:52272
	s_nop 7
	s_nop 1
	ds_write_b32 v218, v38 offset:59136
	ds_write_b32 v218, v39 offset:59664
	ds_write_b32 v218, v40 offset:60192
	ds_write_b32 v218, v41 offset:60720
	s_waitcnt lgkmcnt(0)
	s_barrier
	global_load_dwordx4 v[126:129], v[146:147], off
	global_load_dwordx4 v[122:125], v[154:155], off
	global_load_dwordx4 v[118:121], v[156:157], off
	global_load_dwordx4 v[106:109], v[158:159], off
	global_load_dwordx4 v[98:101], v[160:161], off
	global_load_dwordx4 v[90:93], v[162:163], off
	global_load_dwordx4 v[82:85], v[182:183], off
	global_load_dwordx4 v[74:77], v[184:185], off
	global_load_dwordx4 v[130:133], v[144:145], off
	global_load_dwordx4 v[134:137], v[148:149], off
	global_load_dwordx4 v[220:223], v[144:145], off offset:64
	global_load_dwordx4 v[224:227], v[148:149], off offset:64
	global_load_dwordx4 v[228:231], v[144:145], off offset:128
	global_load_dwordx4 v[232:235], v[148:149], off offset:128
	global_load_dwordx4 v[236:239], v[144:145], off offset:192
	global_load_dwordx4 v[240:243], v[148:149], off offset:192
	s_andn2_b64 vcc, exec, s[40:41]
	s_cbranch_vccnz .Ls5_after_rec
	v_add_u32_e32 v0, 0x800, v189
	ds_read2_b64 v[46:49], v189 offset1:66
	ds_read2_b64 v[42:45], v189 offset0:132 offset1:198
	ds_read2_b64 v[38:41], v0 offset0:8 offset1:74
	ds_read2_b64 v[34:37], v0 offset0:140 offset1:206
	s_mov_b32 s20, 0
	v_mov_b32_e32 v0, v199

.Ls5_after_rec:
	s_waitcnt lgkmcnt(0)
	s_barrier
	s_xor_b64 s[76:77], s[52:53], -1
	s_waitcnt vmcnt(0)
	ds_read_b128 v[2:5], v219
	ds_read_b128 v[6:9], v219 offset:8448
	ds_read_b128 v[10:13], v219 offset:16896
	ds_read_b128 v[14:17], v219 offset:25344
	ds_read_b128 v[18:21], v219 offset:33792
	ds_read_b128 v[22:25], v219 offset:42240
	s_waitcnt lgkmcnt(5)
	v_mfma_f32_16x16x32_bf16 v[114:117], v[2:5], v[130:133], 0
	v_mfma_f32_16x16x32_bf16 v[110:113], v[2:5], v[134:137], 0
	ds_read_b128 v[26:29], v219 offset:50688
	s_waitcnt lgkmcnt(5)
	v_mfma_f32_16x16x32_bf16 v[102:105], v[6:9], v[130:133], 0
	v_mfma_f32_16x16x32_bf16 v[94:97], v[6:9], v[134:137], 0
	ds_read_b128 v[30:33], v219 offset:59136
	s_waitcnt lgkmcnt(5)
	v_mfma_f32_16x16x32_bf16 v[86:89], v[10:13], v[130:133], 0
	v_mfma_f32_16x16x32_bf16 v[78:81], v[10:13], v[134:137], 0
	ds_read_b128 v[2:5], v219 offset:64
	s_waitcnt lgkmcnt(5)
	v_mfma_f32_16x16x32_bf16 v[70:73], v[14:17], v[130:133], 0
	v_mfma_f32_16x16x32_bf16 v[66:69], v[14:17], v[134:137], 0
	ds_read_b128 v[6:9], v219 offset:8512
	s_waitcnt lgkmcnt(5)
	v_mfma_f32_16x16x32_bf16 v[62:65], v[18:21], v[130:133], 0
	v_mfma_f32_16x16x32_bf16 v[58:61], v[18:21], v[134:137], 0
	ds_read_b128 v[10:13], v219 offset:16960
	s_waitcnt lgkmcnt(5)
	v_mfma_f32_16x16x32_bf16 v[54:57], v[22:25], v[130:133], 0
	v_mfma_f32_16x16x32_bf16 v[50:53], v[22:25], v[134:137], 0
	ds_read_b128 v[14:17], v219 offset:25408
	s_waitcnt lgkmcnt(5)
	v_mfma_f32_16x16x32_bf16 v[46:49], v[26:29], v[130:133], 0
	v_mfma_f32_16x16x32_bf16 v[42:45], v[26:29], v[134:137], 0
	ds_read_b128 v[18:21], v219 offset:33856
	s_waitcnt lgkmcnt(5)
	v_mfma_f32_16x16x32_bf16 v[38:41], v[30:33], v[130:133], 0
	v_mfma_f32_16x16x32_bf16 v[34:37], v[30:33], v[134:137], 0
	ds_read_b128 v[22:25], v219 offset:42304
	global_load_dwordx4 v[130:133], v[138:139], off
	s_waitcnt lgkmcnt(5)
	v_mfma_f32_16x16x32_bf16 v[114:117], v[2:5], v[220:223], v[114:117]
	v_mfma_f32_16x16x32_bf16 v[110:113], v[2:5], v[224:227], v[110:113]
	ds_read_b128 v[26:29], v219 offset:50752
	s_waitcnt lgkmcnt(5)
	v_mfma_f32_16x16x32_bf16 v[102:105], v[6:9], v[220:223], v[102:105]
	v_mfma_f32_16x16x32_bf16 v[94:97], v[6:9], v[224:227], v[94:97]
	ds_read_b128 v[30:33], v219 offset:59200
	s_waitcnt lgkmcnt(5)
	v_mfma_f32_16x16x32_bf16 v[86:89], v[10:13], v[220:223], v[86:89]
	v_mfma_f32_16x16x32_bf16 v[78:81], v[10:13], v[224:227], v[78:81]
	ds_read_b128 v[2:5], v219 offset:128
	s_waitcnt lgkmcnt(5)
	v_mfma_f32_16x16x32_bf16 v[70:73], v[14:17], v[220:223], v[70:73]
	v_mfma_f32_16x16x32_bf16 v[66:69], v[14:17], v[224:227], v[66:69]
	ds_read_b128 v[6:9], v219 offset:8576
	s_waitcnt lgkmcnt(5)
	v_mfma_f32_16x16x32_bf16 v[62:65], v[18:21], v[220:223], v[62:65]
	v_mfma_f32_16x16x32_bf16 v[58:61], v[18:21], v[224:227], v[58:61]
	ds_read_b128 v[10:13], v219 offset:17024
	s_waitcnt lgkmcnt(5)
	v_mfma_f32_16x16x32_bf16 v[54:57], v[22:25], v[220:223], v[54:57]
	v_mfma_f32_16x16x32_bf16 v[50:53], v[22:25], v[224:227], v[50:53]
	ds_read_b128 v[14:17], v219 offset:25472
	s_waitcnt lgkmcnt(5)
	v_mfma_f32_16x16x32_bf16 v[46:49], v[26:29], v[220:223], v[46:49]
	v_mfma_f32_16x16x32_bf16 v[42:45], v[26:29], v[224:227], v[42:45]
	ds_read_b128 v[18:21], v219 offset:33920
	s_waitcnt lgkmcnt(5)
	v_mfma_f32_16x16x32_bf16 v[38:41], v[30:33], v[220:223], v[38:41]
	v_mfma_f32_16x16x32_bf16 v[34:37], v[30:33], v[224:227], v[34:37]
	ds_read_b128 v[22:25], v219 offset:42368
	global_load_dwordx4 v[220:223], v[138:139], off offset:64
	s_waitcnt lgkmcnt(5)
	v_mfma_f32_16x16x32_bf16 v[114:117], v[2:5], v[228:231], v[114:117]
	v_mfma_f32_16x16x32_bf16 v[110:113], v[2:5], v[232:235], v[110:113]
	ds_read_b128 v[26:29], v219 offset:50816
	s_waitcnt lgkmcnt(5)
	v_mfma_f32_16x16x32_bf16 v[102:105], v[6:9], v[228:231], v[102:105]
	v_mfma_f32_16x16x32_bf16 v[94:97], v[6:9], v[232:235], v[94:97]
	ds_read_b128 v[30:33], v219 offset:59264
	s_waitcnt lgkmcnt(5)
	v_mfma_f32_16x16x32_bf16 v[86:89], v[10:13], v[228:231], v[86:89]
	v_mfma_f32_16x16x32_bf16 v[78:81], v[10:13], v[232:235], v[78:81]
	ds_read_b128 v[2:5], v219 offset:192
	s_waitcnt lgkmcnt(5)
	v_mfma_f32_16x16x32_bf16 v[70:73], v[14:17], v[228:231], v[70:73]
	v_mfma_f32_16x16x32_bf16 v[66:69], v[14:17], v[232:235], v[66:69]
	ds_read_b128 v[6:9], v219 offset:8640
	s_waitcnt lgkmcnt(5)
	v_mfma_f32_16x16x32_bf16 v[62:65], v[18:21], v[228:231], v[62:65]
	v_mfma_f32_16x16x32_bf16 v[58:61], v[18:21], v[232:235], v[58:61]
	ds_read_b128 v[10:13], v219 offset:17088
	s_waitcnt lgkmcnt(5)
	v_mfma_f32_16x16x32_bf16 v[54:57], v[22:25], v[228:231], v[54:57]
	v_mfma_f32_16x16x32_bf16 v[50:53], v[22:25], v[232:235], v[50:53]
	ds_read_b128 v[14:17], v219 offset:25536
	s_waitcnt lgkmcnt(5)
	v_mfma_f32_16x16x32_bf16 v[46:49], v[26:29], v[228:231], v[46:49]
	v_mfma_f32_16x16x32_bf16 v[42:45], v[26:29], v[232:235], v[42:45]
	ds_read_b128 v[18:21], v219 offset:33984
	s_waitcnt lgkmcnt(5)
	v_mfma_f32_16x16x32_bf16 v[38:41], v[30:33], v[228:231], v[38:41]
	v_mfma_f32_16x16x32_bf16 v[34:37], v[30:33], v[232:235], v[34:37]
	ds_read_b128 v[22:25], v219 offset:42432
	global_load_dwordx4 v[228:231], v[138:139], off offset:128
	s_waitcnt lgkmcnt(5)
	v_mfma_f32_16x16x32_bf16 v[114:117], v[2:5], v[236:239], v[114:117]
	v_mfma_f32_16x16x32_bf16 v[110:113], v[2:5], v[240:243], v[110:113]
	ds_read_b128 v[26:29], v219 offset:50880
	s_waitcnt lgkmcnt(5)
	v_mfma_f32_16x16x32_bf16 v[102:105], v[6:9], v[236:239], v[102:105]
	v_mfma_f32_16x16x32_bf16 v[94:97], v[6:9], v[240:243], v[94:97]
	ds_read_b128 v[30:33], v219 offset:59328
	s_waitcnt lgkmcnt(5)
	v_mfma_f32_16x16x32_bf16 v[86:89], v[10:13], v[236:239], v[86:89]
	v_mfma_f32_16x16x32_bf16 v[78:81], v[10:13], v[240:243], v[78:81]
	ds_read_b128 v[2:5], v197
	s_waitcnt lgkmcnt(5)
	v_mfma_f32_16x16x32_bf16 v[70:73], v[14:17], v[236:239], v[70:73]
	v_mfma_f32_16x16x32_bf16 v[66:69], v[14:17], v[240:243], v[66:69]
	ds_read_b128 v[6:9], v197 offset:8448
	s_waitcnt lgkmcnt(5)
	v_mfma_f32_16x16x32_bf16 v[62:65], v[18:21], v[236:239], v[62:65]
	v_mfma_f32_16x16x32_bf16 v[58:61], v[18:21], v[240:243], v[58:61]
	ds_read_b128 v[10:13], v197 offset:16896
	s_waitcnt lgkmcnt(5)
	v_mfma_f32_16x16x32_bf16 v[54:57], v[22:25], v[236:239], v[54:57]
	v_mfma_f32_16x16x32_bf16 v[50:53], v[22:25], v[240:243], v[50:53]
	ds_read_b128 v[14:17], v197 offset:25344
	s_waitcnt lgkmcnt(5)
	v_mfma_f32_16x16x32_bf16 v[46:49], v[26:29], v[236:239], v[46:49]
	v_mfma_f32_16x16x32_bf16 v[42:45], v[26:29], v[240:243], v[42:45]
	ds_read_b128 v[18:21], v197 offset:33792
	s_waitcnt lgkmcnt(5)
	v_mfma_f32_16x16x32_bf16 v[38:41], v[30:33], v[236:239], v[38:41]
	v_mfma_f32_16x16x32_bf16 v[34:37], v[30:33], v[240:243], v[34:37]
	ds_read_b128 v[22:25], v197 offset:42240
	global_load_dwordx4 v[236:239], v[138:139], off offset:192
	s_cmp_gt_i32 s14, -1
	s_cbranch_scc0 .Ls5_mdone
	s_cmp_gt_i32 s47, -1
	s_cbranch_scc0 .Ls5_m0_one
	s_waitcnt vmcnt(3)
	s_waitcnt lgkmcnt(5)
	v_mfma_f32_16x16x32_bf16 v[110:113], v[2:5], v[126:129], v[110:113]
	v_mfma_f32_16x16x32_bf16 v[114:117], v[2:5], v[130:133], v[114:117]
	ds_read_b128 v[26:29], v197 offset:50688
	s_waitcnt lgkmcnt(5)
	v_mfma_f32_16x16x32_bf16 v[94:97], v[6:9], v[126:129], v[94:97]
	v_mfma_f32_16x16x32_bf16 v[102:105], v[6:9], v[130:133], v[102:105]
	ds_read_b128 v[30:33], v197 offset:59136
	s_waitcnt lgkmcnt(5)
	v_mfma_f32_16x16x32_bf16 v[78:81], v[10:13], v[126:129], v[78:81]
	v_mfma_f32_16x16x32_bf16 v[86:89], v[10:13], v[130:133], v[86:89]
	ds_read_b128 v[2:5], v197 offset:64
	s_waitcnt lgkmcnt(5)
	v_mfma_f32_16x16x32_bf16 v[66:69], v[14:17], v[126:129], v[66:69]
	v_mfma_f32_16x16x32_bf16 v[70:73], v[14:17], v[130:133], v[70:73]
	ds_read_b128 v[6:9], v197 offset:8512
	s_waitcnt lgkmcnt(5)
	v_mfma_f32_16x16x32_bf16 v[58:61], v[18:21], v[126:129], v[58:61]
	v_mfma_f32_16x16x32_bf16 v[62:65], v[18:21], v[130:133], v[62:65]
	ds_read_b128 v[10:13], v197 offset:16960
	s_waitcnt lgkmcnt(5)
	v_mfma_f32_16x16x32_bf16 v[50:53], v[22:25], v[126:129], v[50:53]
	v_mfma_f32_16x16x32_bf16 v[54:57], v[22:25], v[130:133], v[54:57]
	ds_read_b128 v[14:17], v197 offset:25408
	s_waitcnt lgkmcnt(5)
	v_mfma_f32_16x16x32_bf16 v[42:45], v[26:29], v[126:129], v[42:45]
	v_mfma_f32_16x16x32_bf16 v[46:49], v[26:29], v[130:133], v[46:49]
	ds_read_b128 v[18:21], v197 offset:33856
	s_waitcnt lgkmcnt(5)
	v_mfma_f32_16x16x32_bf16 v[34:37], v[30:33], v[126:129], v[34:37]
	v_mfma_f32_16x16x32_bf16 v[38:41], v[30:33], v[130:133], v[38:41]
	ds_read_b128 v[22:25], v197 offset:42304
	s_branch .Ls5_m0_end
.Ls5_m0_one:
	s_waitcnt lgkmcnt(5)
	v_mfma_f32_16x16x32_bf16 v[110:113], v[2:5], v[126:129], v[110:113]
	ds_read_b128 v[26:29], v197 offset:50688
	s_waitcnt lgkmcnt(5)
	v_mfma_f32_16x16x32_bf16 v[94:97], v[6:9], v[126:129], v[94:97]
	ds_read_b128 v[30:33], v197 offset:59136
	s_waitcnt lgkmcnt(5)
	v_mfma_f32_16x16x32_bf16 v[78:81], v[10:13], v[126:129], v[78:81]
	ds_read_b128 v[2:5], v197 offset:64
	s_waitcnt lgkmcnt(5)
	v_mfma_f32_16x16x32_bf16 v[66:69], v[14:17], v[126:129], v[66:69]
	ds_read_b128 v[6:9], v197 offset:8512
	s_waitcnt lgkmcnt(5)
	v_mfma_f32_16x16x32_bf16 v[58:61], v[18:21], v[126:129], v[58:61]
	ds_read_b128 v[10:13], v197 offset:16960
	s_waitcnt lgkmcnt(5)
	v_mfma_f32_16x16x32_bf16 v[50:53], v[22:25], v[126:129], v[50:53]
	ds_read_b128 v[14:17], v197 offset:25408
	s_waitcnt lgkmcnt(5)
	v_mfma_f32_16x16x32_bf16 v[42:45], v[26:29], v[126:129], v[42:45]
	ds_read_b128 v[18:21], v197 offset:33856
	s_waitcnt lgkmcnt(5)
	v_mfma_f32_16x16x32_bf16 v[34:37], v[30:33], v[126:129], v[34:37]
	ds_read_b128 v[22:25], v197 offset:42304
.Ls5_m0_end:
	s_cmp_gt_i32 s14, 1
	s_cbranch_scc0 .Ls5_mdone
	s_cmp_gt_i32 s47, 1
	s_cbranch_scc0 .Ls5_m1_one
	s_waitcnt vmcnt(2)
	s_waitcnt lgkmcnt(5)
	v_mfma_f32_16x16x32_bf16 v[110:113], v[2:5], v[122:125], v[110:113]
	v_mfma_f32_16x16x32_bf16 v[114:117], v[2:5], v[220:223], v[114:117]
	ds_read_b128 v[26:29], v197 offset:50752
	s_waitcnt lgkmcnt(5)
	v_mfma_f32_16x16x32_bf16 v[94:97], v[6:9], v[122:125], v[94:97]
	v_mfma_f32_16x16x32_bf16 v[102:105], v[6:9], v[220:223], v[102:105]
	ds_read_b128 v[30:33], v197 offset:59200
	s_waitcnt lgkmcnt(5)
	v_mfma_f32_16x16x32_bf16 v[78:81], v[10:13], v[122:125], v[78:81]
	v_mfma_f32_16x16x32_bf16 v[86:89], v[10:13], v[220:223], v[86:89]
	ds_read_b128 v[2:5], v197 offset:128
	s_waitcnt lgkmcnt(5)
	v_mfma_f32_16x16x32_bf16 v[66:69], v[14:17], v[122:125], v[66:69]
	v_mfma_f32_16x16x32_bf16 v[70:73], v[14:17], v[220:223], v[70:73]
	ds_read_b128 v[6:9], v197 offset:8576
	s_waitcnt lgkmcnt(5)
	v_mfma_f32_16x16x32_bf16 v[58:61], v[18:21], v[122:125], v[58:61]
	v_mfma_f32_16x16x32_bf16 v[62:65], v[18:21], v[220:223], v[62:65]
	ds_read_b128 v[10:13], v197 offset:17024
	s_waitcnt lgkmcnt(5)
	v_mfma_f32_16x16x32_bf16 v[50:53], v[22:25], v[122:125], v[50:53]
	v_mfma_f32_16x16x32_bf16 v[54:57], v[22:25], v[220:223], v[54:57]
	ds_read_b128 v[14:17], v197 offset:25472
	s_waitcnt lgkmcnt(5)
	v_mfma_f32_16x16x32_bf16 v[42:45], v[26:29], v[122:125], v[42:45]
	v_mfma_f32_16x16x32_bf16 v[46:49], v[26:29], v[220:223], v[46:49]
	ds_read_b128 v[18:21], v197 offset:33920
	s_waitcnt lgkmcnt(5)
	v_mfma_f32_16x16x32_bf16 v[34:37], v[30:33], v[122:125], v[34:37]
	v_mfma_f32_16x16x32_bf16 v[38:41], v[30:33], v[220:223], v[38:41]
	ds_read_b128 v[22:25], v197 offset:42368
	s_branch .Ls5_m1_end
.Ls5_m1_one:
	s_waitcnt lgkmcnt(5)
	v_mfma_f32_16x16x32_bf16 v[110:113], v[2:5], v[122:125], v[110:113]
	ds_read_b128 v[26:29], v197 offset:50752
	s_waitcnt lgkmcnt(5)
	v_mfma_f32_16x16x32_bf16 v[94:97], v[6:9], v[122:125], v[94:97]
	ds_read_b128 v[30:33], v197 offset:59200
	s_waitcnt lgkmcnt(5)
	v_mfma_f32_16x16x32_bf16 v[78:81], v[10:13], v[122:125], v[78:81]
	ds_read_b128 v[2:5], v197 offset:128
	s_waitcnt lgkmcnt(5)
	v_mfma_f32_16x16x32_bf16 v[66:69], v[14:17], v[122:125], v[66:69]
	ds_read_b128 v[6:9], v197 offset:8576
	s_waitcnt lgkmcnt(5)
	v_mfma_f32_16x16x32_bf16 v[58:61], v[18:21], v[122:125], v[58:61]
	ds_read_b128 v[10:13], v197 offset:17024
	s_waitcnt lgkmcnt(5)
	v_mfma_f32_16x16x32_bf16 v[50:53], v[22:25], v[122:125], v[50:53]
	ds_read_b128 v[14:17], v197 offset:25472
	s_waitcnt lgkmcnt(5)
	v_mfma_f32_16x16x32_bf16 v[42:45], v[26:29], v[122:125], v[42:45]
	ds_read_b128 v[18:21], v197 offset:33920
	s_waitcnt lgkmcnt(5)
	v_mfma_f32_16x16x32_bf16 v[34:37], v[30:33], v[122:125], v[34:37]
	ds_read_b128 v[22:25], v197 offset:42368
.Ls5_m1_end:
	s_cmp_gt_i32 s14, 3
	s_cbranch_scc0 .Ls5_mdone
	s_cmp_gt_i32 s47, 3
	s_cbranch_scc0 .Ls5_m2_one
	s_waitcnt vmcnt(1)
	s_waitcnt lgkmcnt(5)
	v_mfma_f32_16x16x32_bf16 v[110:113], v[2:5], v[118:121], v[110:113]
	v_mfma_f32_16x16x32_bf16 v[114:117], v[2:5], v[228:231], v[114:117]
	ds_read_b128 v[26:29], v197 offset:50816
	s_waitcnt lgkmcnt(5)
	v_mfma_f32_16x16x32_bf16 v[94:97], v[6:9], v[118:121], v[94:97]
	v_mfma_f32_16x16x32_bf16 v[102:105], v[6:9], v[228:231], v[102:105]
	ds_read_b128 v[30:33], v197 offset:59264
	s_waitcnt lgkmcnt(5)
	v_mfma_f32_16x16x32_bf16 v[78:81], v[10:13], v[118:121], v[78:81]
	v_mfma_f32_16x16x32_bf16 v[86:89], v[10:13], v[228:231], v[86:89]
	ds_read_b128 v[2:5], v197 offset:192
	s_waitcnt lgkmcnt(5)
	v_mfma_f32_16x16x32_bf16 v[66:69], v[14:17], v[118:121], v[66:69]
	v_mfma_f32_16x16x32_bf16 v[70:73], v[14:17], v[228:231], v[70:73]
	ds_read_b128 v[6:9], v197 offset:8640
	s_waitcnt lgkmcnt(5)
	v_mfma_f32_16x16x32_bf16 v[58:61], v[18:21], v[118:121], v[58:61]
	v_mfma_f32_16x16x32_bf16 v[62:65], v[18:21], v[228:231], v[62:65]
	ds_read_b128 v[10:13], v197 offset:17088
	s_waitcnt lgkmcnt(5)
	v_mfma_f32_16x16x32_bf16 v[50:53], v[22:25], v[118:121], v[50:53]
	v_mfma_f32_16x16x32_bf16 v[54:57], v[22:25], v[228:231], v[54:57]
	ds_read_b128 v[14:17], v197 offset:25536
	s_waitcnt lgkmcnt(5)
	v_mfma_f32_16x16x32_bf16 v[42:45], v[26:29], v[118:121], v[42:45]
	v_mfma_f32_16x16x32_bf16 v[46:49], v[26:29], v[228:231], v[46:49]
	ds_read_b128 v[18:21], v197 offset:33984
	s_waitcnt lgkmcnt(5)
	v_mfma_f32_16x16x32_bf16 v[34:37], v[30:33], v[118:121], v[34:37]
	v_mfma_f32_16x16x32_bf16 v[38:41], v[30:33], v[228:231], v[38:41]
	ds_read_b128 v[22:25], v197 offset:42432
	s_branch .Ls5_m2_end
.Ls5_m2_one:
	s_waitcnt lgkmcnt(5)
	v_mfma_f32_16x16x32_bf16 v[110:113], v[2:5], v[118:121], v[110:113]
	ds_read_b128 v[26:29], v197 offset:50816
	s_waitcnt lgkmcnt(5)
	v_mfma_f32_16x16x32_bf16 v[94:97], v[6:9], v[118:121], v[94:97]
	ds_read_b128 v[30:33], v197 offset:59264
	s_waitcnt lgkmcnt(5)
	v_mfma_f32_16x16x32_bf16 v[78:81], v[10:13], v[118:121], v[78:81]
	ds_read_b128 v[2:5], v197 offset:192
	s_waitcnt lgkmcnt(5)
	v_mfma_f32_16x16x32_bf16 v[66:69], v[14:17], v[118:121], v[66:69]
	ds_read_b128 v[6:9], v197 offset:8640
	s_waitcnt lgkmcnt(5)
	v_mfma_f32_16x16x32_bf16 v[58:61], v[18:21], v[118:121], v[58:61]
	ds_read_b128 v[10:13], v197 offset:17088
	s_waitcnt lgkmcnt(5)
	v_mfma_f32_16x16x32_bf16 v[50:53], v[22:25], v[118:121], v[50:53]
	ds_read_b128 v[14:17], v197 offset:25536
	s_waitcnt lgkmcnt(5)
	v_mfma_f32_16x16x32_bf16 v[42:45], v[26:29], v[118:121], v[42:45]
	ds_read_b128 v[18:21], v197 offset:33984
	s_waitcnt lgkmcnt(5)
	v_mfma_f32_16x16x32_bf16 v[34:37], v[30:33], v[118:121], v[34:37]
	ds_read_b128 v[22:25], v197 offset:42432
.Ls5_m2_end:
	s_cmp_gt_i32 s14, 5
	s_cbranch_scc0 .Ls5_mdone
	s_cmp_gt_i32 s47, 5
	s_cbranch_scc0 .Ls5_m3_one
	s_waitcnt vmcnt(0)
	s_waitcnt lgkmcnt(5)
	v_mfma_f32_16x16x32_bf16 v[110:113], v[2:5], v[106:109], v[110:113]
	v_mfma_f32_16x16x32_bf16 v[114:117], v[2:5], v[236:239], v[114:117]
	ds_read_b128 v[26:29], v197 offset:50880
	s_waitcnt lgkmcnt(5)
	v_mfma_f32_16x16x32_bf16 v[94:97], v[6:9], v[106:109], v[94:97]
	v_mfma_f32_16x16x32_bf16 v[102:105], v[6:9], v[236:239], v[102:105]
	ds_read_b128 v[30:33], v197 offset:59328
	s_waitcnt lgkmcnt(5)
	v_mfma_f32_16x16x32_bf16 v[78:81], v[10:13], v[106:109], v[78:81]
	v_mfma_f32_16x16x32_bf16 v[86:89], v[10:13], v[236:239], v[86:89]
	ds_read_b128 v[2:5], v197 offset:256
	s_waitcnt lgkmcnt(5)
	v_mfma_f32_16x16x32_bf16 v[66:69], v[14:17], v[106:109], v[66:69]
	v_mfma_f32_16x16x32_bf16 v[70:73], v[14:17], v[236:239], v[70:73]
	ds_read_b128 v[6:9], v197 offset:8704
	s_waitcnt lgkmcnt(5)
	v_mfma_f32_16x16x32_bf16 v[58:61], v[18:21], v[106:109], v[58:61]
	v_mfma_f32_16x16x32_bf16 v[62:65], v[18:21], v[236:239], v[62:65]
	ds_read_b128 v[10:13], v197 offset:17152
	s_waitcnt lgkmcnt(5)
	v_mfma_f32_16x16x32_bf16 v[50:53], v[22:25], v[106:109], v[50:53]
	v_mfma_f32_16x16x32_bf16 v[54:57], v[22:25], v[236:239], v[54:57]
	ds_read_b128 v[14:17], v197 offset:25600
	s_waitcnt lgkmcnt(5)
	v_mfma_f32_16x16x32_bf16 v[42:45], v[26:29], v[106:109], v[42:45]
	v_mfma_f32_16x16x32_bf16 v[46:49], v[26:29], v[236:239], v[46:49]
	ds_read_b128 v[18:21], v197 offset:34048
	s_waitcnt lgkmcnt(5)
	v_mfma_f32_16x16x32_bf16 v[34:37], v[30:33], v[106:109], v[34:37]
	v_mfma_f32_16x16x32_bf16 v[38:41], v[30:33], v[236:239], v[38:41]
	ds_read_b128 v[22:25], v197 offset:42496
	s_branch .Ls5_m3_end
.Ls5_m3_one:
	s_waitcnt lgkmcnt(5)
	v_mfma_f32_16x16x32_bf16 v[110:113], v[2:5], v[106:109], v[110:113]
	ds_read_b128 v[26:29], v197 offset:50880
	s_waitcnt lgkmcnt(5)
	v_mfma_f32_16x16x32_bf16 v[94:97], v[6:9], v[106:109], v[94:97]
	ds_read_b128 v[30:33], v197 offset:59328
	s_waitcnt lgkmcnt(5)
	v_mfma_f32_16x16x32_bf16 v[78:81], v[10:13], v[106:109], v[78:81]
	ds_read_b128 v[2:5], v197 offset:256
	s_waitcnt lgkmcnt(5)
	v_mfma_f32_16x16x32_bf16 v[66:69], v[14:17], v[106:109], v[66:69]
	ds_read_b128 v[6:9], v197 offset:8704
	s_waitcnt lgkmcnt(5)
	v_mfma_f32_16x16x32_bf16 v[58:61], v[18:21], v[106:109], v[58:61]
	ds_read_b128 v[10:13], v197 offset:17152
	s_waitcnt lgkmcnt(5)
	v_mfma_f32_16x16x32_bf16 v[50:53], v[22:25], v[106:109], v[50:53]
	ds_read_b128 v[14:17], v197 offset:25600
	s_waitcnt lgkmcnt(5)
	v_mfma_f32_16x16x32_bf16 v[42:45], v[26:29], v[106:109], v[42:45]
	ds_read_b128 v[18:21], v197 offset:34048
	s_waitcnt lgkmcnt(5)
	v_mfma_f32_16x16x32_bf16 v[34:37], v[30:33], v[106:109], v[34:37]
	ds_read_b128 v[22:25], v197 offset:42496
.Ls5_m3_end:
	s_cmp_gt_i32 s14, 7
	s_cbranch_scc0 .Ls5_mdone
	s_waitcnt lgkmcnt(5)
	v_mfma_f32_16x16x32_bf16 v[110:113], v[2:5], v[98:101], v[110:113]
	ds_read_b128 v[26:29], v197 offset:50944
	s_waitcnt lgkmcnt(5)
	v_mfma_f32_16x16x32_bf16 v[94:97], v[6:9], v[98:101], v[94:97]
	ds_read_b128 v[30:33], v197 offset:59392
	s_waitcnt lgkmcnt(5)
	v_mfma_f32_16x16x32_bf16 v[78:81], v[10:13], v[98:101], v[78:81]
	ds_read_b128 v[2:5], v197 offset:320
	s_waitcnt lgkmcnt(5)
	v_mfma_f32_16x16x32_bf16 v[66:69], v[14:17], v[98:101], v[66:69]
	ds_read_b128 v[6:9], v197 offset:8768
	s_waitcnt lgkmcnt(5)
	v_mfma_f32_16x16x32_bf16 v[58:61], v[18:21], v[98:101], v[58:61]
	ds_read_b128 v[10:13], v197 offset:17216
	s_waitcnt lgkmcnt(5)
	v_mfma_f32_16x16x32_bf16 v[50:53], v[22:25], v[98:101], v[50:53]
	ds_read_b128 v[14:17], v197 offset:25664
	s_waitcnt lgkmcnt(5)
	v_mfma_f32_16x16x32_bf16 v[42:45], v[26:29], v[98:101], v[42:45]
	ds_read_b128 v[18:21], v197 offset:34112
	s_waitcnt lgkmcnt(5)
	v_mfma_f32_16x16x32_bf16 v[34:37], v[30:33], v[98:101], v[34:37]
	ds_read_b128 v[22:25], v197 offset:42560
	s_cmp_gt_i32 s14, 9
	s_cbranch_scc0 .Ls5_mdone
	s_waitcnt lgkmcnt(5)
	v_mfma_f32_16x16x32_bf16 v[110:113], v[2:5], v[90:93], v[110:113]
	ds_read_b128 v[26:29], v197 offset:51008
	s_waitcnt lgkmcnt(5)
	v_mfma_f32_16x16x32_bf16 v[94:97], v[6:9], v[90:93], v[94:97]
	ds_read_b128 v[30:33], v197 offset:59456
	s_waitcnt lgkmcnt(5)
	v_mfma_f32_16x16x32_bf16 v[78:81], v[10:13], v[90:93], v[78:81]
	ds_read_b128 v[2:5], v197 offset:384
	s_waitcnt lgkmcnt(5)
	v_mfma_f32_16x16x32_bf16 v[66:69], v[14:17], v[90:93], v[66:69]
	ds_read_b128 v[6:9], v197 offset:8832
	s_waitcnt lgkmcnt(5)
	v_mfma_f32_16x16x32_bf16 v[58:61], v[18:21], v[90:93], v[58:61]
	ds_read_b128 v[10:13], v197 offset:17280
	s_waitcnt lgkmcnt(5)
	v_mfma_f32_16x16x32_bf16 v[50:53], v[22:25], v[90:93], v[50:53]
	ds_read_b128 v[14:17], v197 offset:25728
	s_waitcnt lgkmcnt(5)
	v_mfma_f32_16x16x32_bf16 v[42:45], v[26:29], v[90:93], v[42:45]
	ds_read_b128 v[18:21], v197 offset:34176
	s_waitcnt lgkmcnt(5)
	v_mfma_f32_16x16x32_bf16 v[34:37], v[30:33], v[90:93], v[34:37]
	ds_read_b128 v[22:25], v197 offset:42624
	s_cmp_gt_i32 s14, 11
	s_cbranch_scc0 .Ls5_mdone
	s_waitcnt lgkmcnt(5)
	v_mfma_f32_16x16x32_bf16 v[110:113], v[2:5], v[82:85], v[110:113]
	ds_read_b128 v[26:29], v197 offset:51072
	s_waitcnt lgkmcnt(5)
	v_mfma_f32_16x16x32_bf16 v[94:97], v[6:9], v[82:85], v[94:97]
	ds_read_b128 v[30:33], v197 offset:59520
	s_waitcnt lgkmcnt(5)
	v_mfma_f32_16x16x32_bf16 v[78:81], v[10:13], v[82:85], v[78:81]
	ds_read_b128 v[2:5], v197 offset:448
	s_waitcnt lgkmcnt(5)
	v_mfma_f32_16x16x32_bf16 v[66:69], v[14:17], v[82:85], v[66:69]
	ds_read_b128 v[6:9], v197 offset:8896
	s_waitcnt lgkmcnt(5)
	v_mfma_f32_16x16x32_bf16 v[58:61], v[18:21], v[82:85], v[58:61]
	ds_read_b128 v[10:13], v197 offset:17344
	s_waitcnt lgkmcnt(5)
	v_mfma_f32_16x16x32_bf16 v[50:53], v[22:25], v[82:85], v[50:53]
	ds_read_b128 v[14:17], v197 offset:25792
	s_waitcnt lgkmcnt(5)
	v_mfma_f32_16x16x32_bf16 v[42:45], v[26:29], v[82:85], v[42:45]
	ds_read_b128 v[18:21], v197 offset:34240
	s_waitcnt lgkmcnt(5)
	v_mfma_f32_16x16x32_bf16 v[34:37], v[30:33], v[82:85], v[34:37]
	ds_read_b128 v[22:25], v197 offset:42688
	s_cmp_gt_i32 s14, 13
	s_cbranch_scc0 .Ls5_mdone
	s_waitcnt lgkmcnt(5)
	v_mfma_f32_16x16x32_bf16 v[110:113], v[2:5], v[74:77], v[110:113]
	ds_read_b128 v[26:29], v197 offset:51136
	s_waitcnt lgkmcnt(5)
	v_mfma_f32_16x16x32_bf16 v[94:97], v[6:9], v[74:77], v[94:97]
	ds_read_b128 v[30:33], v197 offset:59584
	s_waitcnt lgkmcnt(5)
	v_mfma_f32_16x16x32_bf16 v[78:81], v[10:13], v[74:77], v[78:81]
	s_waitcnt lgkmcnt(4)
	v_mfma_f32_16x16x32_bf16 v[66:69], v[14:17], v[74:77], v[66:69]
	s_waitcnt lgkmcnt(3)
	v_mfma_f32_16x16x32_bf16 v[58:61], v[18:21], v[74:77], v[58:61]
	s_waitcnt lgkmcnt(2)
	v_mfma_f32_16x16x32_bf16 v[50:53], v[22:25], v[74:77], v[50:53]
	s_waitcnt lgkmcnt(1)
	v_mfma_f32_16x16x32_bf16 v[42:45], v[26:29], v[74:77], v[42:45]
	s_waitcnt lgkmcnt(0)
	v_mfma_f32_16x16x32_bf16 v[34:37], v[30:33], v[74:77], v[34:37]
.Ls5_mdone:
	s_branch .LBB0_655
